# R2/R3 norm half: (x*rstd) * (gpre*scale + gpre) + shift, one fma builds gpre*(1+scale) (two packed ops fewer per 4 columns)
# baseline (speedup 1.0000x reference)
.Lr2_slow_proc:
	s_barrier
	v_add_u32_e32 v37, s93, v160
	ds_read_b128 v[64:67], v37
	ds_read_b128 v[68:71], v37 offset:1024
	ds_read_b128 v[72:75], v37 offset:2048
	ds_read_b128 v[76:79], v37 offset:3072
	ds_read_b128 v[80:83], v37 offset:4096
	ds_read_b128 v[84:87], v37 offset:5120
	ds_read_b128 v[88:91], v37 offset:6144
	ds_read_b128 v[92:95], v37 offset:7168
	v_lshlrev_b32_e32 v172, 16, v54
	v_and_b32_e32 v173, 0xffff0000, v54
	v_lshlrev_b32_e32 v174, 16, v55
	v_and_b32_e32 v175, 0xffff0000, v55
	v_pk_mul_f32 v[166:167], v[172:173], v[172:173]
	v_pk_mul_f32 v[168:169], v[174:175], v[174:175]
	v_lshlrev_b32_e32 v176, 16, v52
	v_and_b32_e32 v177, 0xffff0000, v52
	v_lshlrev_b32_e32 v178, 16, v53
	v_and_b32_e32 v179, 0xffff0000, v53
	v_pk_fma_f32 v[166:167], v[176:177], v[176:177], v[166:167]
	v_pk_fma_f32 v[168:169], v[178:179], v[178:179], v[168:169]
	v_lshlrev_b32_e32 v180, 16, v50
	v_and_b32_e32 v181, 0xffff0000, v50
	v_lshlrev_b32_e32 v182, 16, v51
	v_and_b32_e32 v183, 0xffff0000, v51
	v_pk_fma_f32 v[166:167], v[180:181], v[180:181], v[166:167]
	v_pk_fma_f32 v[168:169], v[182:183], v[182:183], v[168:169]
	v_lshlrev_b32_e32 v184, 16, v48
	v_and_b32_e32 v185, 0xffff0000, v48
	v_lshlrev_b32_e32 v186, 16, v49
	v_and_b32_e32 v187, 0xffff0000, v49
	v_pk_fma_f32 v[166:167], v[184:185], v[184:185], v[166:167]
	v_pk_fma_f32 v[168:169], v[186:187], v[186:187], v[168:169]
	v_pk_add_f32 v[166:167], v[166:167], v[168:169]
	s_nop 0
	v_add_f32_e32 v164, v166, v167
	v_mov_b32_e32 v165, v164
	s_nop 1
	v_permlane32_swap_b32_e32 v165, v164
	v_add_f32_e32 v164, v164, v165
	v_mov_b32_e32 v165, v164
	s_nop 1
	v_permlane16_swap_b32_e32 v165, v164
	v_add_f32_e32 v164, v164, v165
	s_nop 1
	v_add_f32_dpp v164, v164, v164 row_ror:8 row_mask:0xf bank_mask:0xf
	s_nop 1
	v_add_f32_dpp v164, v164, v164 row_ror:4 row_mask:0xf bank_mask:0xf
	s_nop 1
	v_add_f32_dpp v164, v164, v164 row_ror:2 row_mask:0xf bank_mask:0xf
	s_nop 1
	v_add_f32_dpp v164, v164, v164 row_ror:1 row_mask:0xf bank_mask:0xf
	s_nop 0
	v_fmamk_f32 v164, v164, 0x3a800000, v200
	v_rsq_f32_e32 v164, v164
	s_nop 0
	v_pk_mul_f32 v[172:173], v[172:173], v[164:165] op_sel_hi:[1,0]
	v_pk_mul_f32 v[174:175], v[174:175], v[164:165] op_sel_hi:[1,0]
	v_pk_mul_f32 v[172:173], v[218:219], v[172:173]
	v_pk_mul_f32 v[174:175], v[220:221], v[174:175]
	s_waitcnt lgkmcnt(7)
	v_pk_fma_f32 v[12:13], v[64:65], v[172:173], v[12:13]
	v_pk_fma_f32 v[14:15], v[66:67], v[174:175], v[14:15]
	global_store_dwordx4 v160, v[12:15], s[40:41] nt
	v_pk_mul_f32 v[176:177], v[176:177], v[164:165] op_sel_hi:[1,0]
	v_pk_mul_f32 v[178:179], v[178:179], v[164:165] op_sel_hi:[1,0]
	v_pk_mul_f32 v[176:177], v[222:223], v[176:177]
	v_pk_mul_f32 v[178:179], v[224:225], v[178:179]
	s_waitcnt lgkmcnt(6)
	v_pk_fma_f32 v[8:9], v[68:69], v[176:177], v[8:9]
	v_pk_fma_f32 v[10:11], v[70:71], v[178:179], v[10:11]
	global_store_dwordx4 v160, v[8:11], s[40:41] offset:1024 nt
	v_pk_mul_f32 v[180:181], v[180:181], v[164:165] op_sel_hi:[1,0]
	v_pk_mul_f32 v[182:183], v[182:183], v[164:165] op_sel_hi:[1,0]
	v_pk_mul_f32 v[180:181], v[226:227], v[180:181]
	v_pk_mul_f32 v[182:183], v[228:229], v[182:183]
	s_waitcnt lgkmcnt(5)
	v_pk_fma_f32 v[4:5], v[72:73], v[180:181], v[4:5]
	v_pk_fma_f32 v[6:7], v[74:75], v[182:183], v[6:7]
	global_store_dwordx4 v160, v[4:7], s[40:41] offset:2048 nt
	v_pk_mul_f32 v[184:185], v[184:185], v[164:165] op_sel_hi:[1,0]
	v_pk_mul_f32 v[186:187], v[186:187], v[164:165] op_sel_hi:[1,0]
	v_pk_mul_f32 v[184:185], v[230:231], v[184:185]
	v_pk_mul_f32 v[186:187], v[232:233], v[186:187]
	s_waitcnt lgkmcnt(4)
	v_pk_fma_f32 v[0:1], v[76:77], v[184:185], v[0:1]
	v_pk_fma_f32 v[2:3], v[78:79], v[186:187], v[2:3]
	global_store_dwordx4 v160, v[0:3], s[40:41] offset:3072 nt
	s_waitcnt lgkmcnt(0)
	ds_read_b128 v[172:175], v37 offset:8192
	ds_read_b128 v[176:179], v37 offset:9216
	ds_read_b128 v[180:183], v37 offset:10240
	ds_read_b128 v[184:187], v37 offset:11264
	ds_read_b128 v[188:191], v37 offset:12288
	ds_read_b128 v[192:195], v37 offset:13312
	ds_read_b128 v[196:199], v37 offset:14336
	ds_read_b128 v[96:99], v37 offset:15360
	ds_read_b128 v[64:67], v37 offset:16384
	ds_read_b128 v[68:71], v37 offset:17408
	ds_read_b128 v[72:75], v37 offset:18432
	ds_read_b128 v[76:79], v37 offset:19456
	v_add_co_u32_e32 v250, vcc, 0xfbc00000, v46
	v_addc_co_u32_e32 v251, vcc, -1, v47, vcc
	v_pk_mul_f32 v[166:167], v[12:13], v[12:13]
	v_pk_mul_f32 v[168:169], v[14:15], v[14:15]
	v_pk_fma_f32 v[166:167], v[8:9], v[8:9], v[166:167]
	v_pk_fma_f32 v[168:169], v[10:11], v[10:11], v[168:169]
	v_pk_fma_f32 v[166:167], v[4:5], v[4:5], v[166:167]
	v_pk_fma_f32 v[168:169], v[6:7], v[6:7], v[168:169]
	v_pk_fma_f32 v[166:167], v[0:1], v[0:1], v[166:167]
	v_pk_fma_f32 v[168:169], v[2:3], v[2:3], v[168:169]
	v_pk_add_f32 v[166:167], v[166:167], v[168:169]
	s_nop 0
	v_add_f32_e32 v164, v166, v167
	v_mov_b32_e32 v165, v164
	s_nop 1
	v_permlane32_swap_b32_e32 v165, v164
	v_add_f32_e32 v164, v164, v165
	v_mov_b32_e32 v165, v164
	s_nop 1
	v_permlane16_swap_b32_e32 v165, v164
	v_add_f32_e32 v164, v164, v165
	s_nop 1
	v_add_f32_dpp v164, v164, v164 row_ror:8 row_mask:0xf bank_mask:0xf
	s_nop 1
	v_add_f32_dpp v164, v164, v164 row_ror:4 row_mask:0xf bank_mask:0xf
	s_nop 1
	v_add_f32_dpp v164, v164, v164 row_ror:2 row_mask:0xf bank_mask:0xf
	s_nop 1
	v_add_f32_dpp v164, v164, v164 row_ror:1 row_mask:0xf bank_mask:0xf
	s_nop 0
	v_fmamk_f32 v164, v164, 0x3a800000, v200
	v_rsq_f32_e32 v164, v164
	s_nop 0
	v_pk_mul_f32 v[12:13], v[12:13], v[164:165] op_sel_hi:[1,0]
	v_pk_mul_f32 v[14:15], v[14:15], v[164:165] op_sel_hi:[1,0]
	s_waitcnt lgkmcnt(11)
	v_pk_fma_f32 v[172:173], v[234:235], v[172:173], v[234:235]
	v_pk_fma_f32 v[174:175], v[236:237], v[174:175], v[236:237]
	v_pk_fma_f32 v[12:13], v[172:173], v[12:13], v[80:81]
	v_pk_fma_f32 v[14:15], v[174:175], v[14:15], v[82:83]
	v_cvt_pk_bf16_f32 v12, v12, v13
	v_cvt_pk_bf16_f32 v13, v14, v15
	global_store_dwordx2 v[250:251], v[12:13], off offset:-1536
	ds_read_b128 v[80:83], v37 offset:20480
	v_pk_mul_f32 v[8:9], v[8:9], v[164:165] op_sel_hi:[1,0]
	v_pk_mul_f32 v[10:11], v[10:11], v[164:165] op_sel_hi:[1,0]
	s_waitcnt lgkmcnt(11)
	v_pk_fma_f32 v[176:177], v[238:239], v[176:177], v[238:239]
	v_pk_fma_f32 v[178:179], v[240:241], v[178:179], v[240:241]
	v_pk_fma_f32 v[8:9], v[176:177], v[8:9], v[84:85]
	v_pk_fma_f32 v[10:11], v[178:179], v[10:11], v[86:87]
	v_cvt_pk_bf16_f32 v8, v8, v9
	v_cvt_pk_bf16_f32 v9, v10, v11
	global_store_dwordx2 v[250:251], v[8:9], off offset:-1024
	ds_read_b128 v[84:87], v37 offset:21504
	v_pk_mul_f32 v[4:5], v[4:5], v[164:165] op_sel_hi:[1,0]
	v_pk_mul_f32 v[6:7], v[6:7], v[164:165] op_sel_hi:[1,0]
	s_waitcnt lgkmcnt(11)
	v_pk_fma_f32 v[180:181], v[242:243], v[180:181], v[242:243]
	v_pk_fma_f32 v[182:183], v[244:245], v[182:183], v[244:245]
	v_pk_fma_f32 v[4:5], v[180:181], v[4:5], v[88:89]
	v_pk_fma_f32 v[6:7], v[182:183], v[6:7], v[90:91]
	v_cvt_pk_bf16_f32 v4, v4, v5
	v_cvt_pk_bf16_f32 v5, v6, v7
	global_store_dwordx2 v[250:251], v[4:5], off offset:-512
	ds_read_b128 v[88:91], v37 offset:22528
	v_pk_mul_f32 v[0:1], v[0:1], v[164:165] op_sel_hi:[1,0]
	v_pk_mul_f32 v[2:3], v[2:3], v[164:165] op_sel_hi:[1,0]
	s_waitcnt lgkmcnt(11)
	v_pk_fma_f32 v[184:185], v[246:247], v[184:185], v[246:247]
	v_pk_fma_f32 v[186:187], v[248:249], v[186:187], v[248:249]
	v_pk_fma_f32 v[0:1], v[184:185], v[0:1], v[92:93]
	v_pk_fma_f32 v[2:3], v[186:187], v[2:3], v[94:95]
	v_cvt_pk_bf16_f32 v0, v0, v1
	v_cvt_pk_bf16_f32 v1, v2, v3
	global_store_dwordx2 v[250:251], v[0:1], off
	ds_read_b128 v[92:95], v37 offset:23552
	s_waitcnt vmcnt(8)
	s_mov_b32 s99, 0
	s_add_i32 s72, s13, s48
	s_cmp_gt_i32 s72, 0x87ff
	s_cbranch_scc1 .Lr2_slow_nopf
	s_add_i32 s8, s44, s72
	s_cmp_lt_i32 s8, 0x8800
	s_cbranch_scc0 .Lr2_slow_nopf
	s_mov_b32 s41, s72
	s_mul_hi_i32 s6, s41, 0x78787879
	s_lshr_b32 s7, s6, 31
	s_ashr_i32 s6, s6, 11
	s_add_i32 s6, s6, s7
	s_mul_i32 s7, s6, 0xffffef00
	s_add_i32 s7, s41, s7
	s_cmpk_gt_i32 s7, 0xff
	s_cselect_b64 s[50:51], -1, 0
	s_mul_hi_i32 s9, s8, 0x78787879
	s_lshr_b32 s25, s9, 31
	s_ashr_i32 s9, s9, 11
	s_add_i32 s9, s9, s25
	s_mul_i32 s25, s9, 0xffffef00
	s_add_i32 s25, s8, s25
	s_cmpk_gt_i32 s25, 0xff
	s_cselect_b64 s[52:53], -1, 0
	s_and_b64 s[46:47], s[50:51], s[52:53]
	s_or_b64 s[46:47], s[46:47], s[62:63]
	s_cmp_lg_u64 s[46:47], 0
	s_cbranch_scc0 .Lr2_slow_nopf
	s_add_i32 s72, s7, 0xffffff00
	s_cmp_lg_u64 s[50:51], 0
	s_cselect_b32 s27, s4, s49
	s_cselect_b32 s32, s5, s55
	s_cselect_b32 s37, 24, 20
	s_cselect_b32 s72, s72, s7
	s_cselect_b32 s85, s6, 8
	s_mov_b32 s40, s6
	s_mov_b32 s41, 0
	s_lshl_b64 s[40:41], s[40:41], s37
	s_add_u32 s40, s27, s40
	s_addc_u32 s41, s32, s41
	s_lshl_b32 s72, s72, 12
	s_add_u32 s40, s40, s72
	s_addc_u32 s41, s41, 0
	s_add_i32 s27, s85, s3
	s_mul_hi_i32 s32, s27, 0x6000
	s_mulk_i32 s27, 0x6000
	s_add_u32 s66, s34, s27
	s_addc_u32 s67, s35, s32
	s_add_u32 s66, s66, 0x2000
	s_addc_u32 s67, s67, 0
	s_add_i32 s27, s85, s3
	s_mul_hi_i32 s32, s27, 0x6000
	s_mulk_i32 s27, 0x6000
	s_add_u32 s38, s34, s27
	s_addc_u32 s39, s35, s32
	s_add_u32 s38, s38, 0x3000
	s_addc_u32 s39, s39, 0
	s_add_u32 s46, s38, 0x1000
	s_addc_u32 s47, s39, 0
	s_cmp_lg_u64 s[50:51], 0
	s_cselect_b32 s22, s68, s70
	s_cselect_b32 s23, s69, s71
	s_add_u32 s22, s22, s40
	s_addc_u32 s23, s23, s41
	s_mov_b64 s[6:7], s[52:53]
	s_cmp_lg_u64 s[6:7], 0
	s_cselect_b32 s85, s9, 8
	s_add_i32 s27, s85, s3
	s_mul_hi_i32 s32, s27, 0x6000
	s_mulk_i32 s27, 0x6000
	s_add_u32 s10, s34, s27
	s_addc_u32 s11, s35, s32
	s_add_u32 s10, s10, 0x2000
	s_addc_u32 s11, s11, 0
	s_add_i32 s27, s85, s3
	s_mul_hi_i32 s32, s27, 0x6000
	s_mulk_i32 s27, 0x6000
	s_add_u32 s50, s34, s27
	s_addc_u32 s51, s35, s32
	s_add_u32 s50, s50, 0x3000
	s_addc_u32 s51, s51, 0
	s_add_u32 s52, s50, 0x1000
	s_addc_u32 s53, s51, 0
	s_xor_b32 s25, s93, 0x6000
	v_lshl_add_u64 v[250:251], v[46:47], 0, s[74:75]
	global_load_dwordx4 v[12:15], v160, s[22:23] nt
	global_load_dwordx4 v[8:11], v160, s[22:23] offset:1024 nt
	global_load_dwordx4 v[4:7], v160, s[22:23] offset:2048 nt
	global_load_dwordx4 v[0:3], v160, s[22:23] offset:3072 nt
	global_load_dwordx2 v[54:55], v[250:251], off offset:-1536 nt
	global_load_dwordx2 v[52:53], v[250:251], off offset:-1024 nt
	global_load_dwordx2 v[50:51], v[250:251], off offset:-512 nt
	global_load_dwordx2 v[48:49], v[250:251], off nt
	s_and_b32 s72, s13, 7
	s_and_b32 s85, s72, 3
	s_lshl_b32 s85, s85, 10
	s_lshl_b32 s37, s72, 10
	s_add_i32 s37, s37, s25
	s_cmp_lt_u32 s72, 4
	s_cselect_b32 s6, s66, s38
	s_cselect_b32 s7, s67, s39
	s_cselect_b32 s8, s46, s10
	s_cselect_b32 s9, s47, s11
	s_cselect_b32 s26, s50, s52
	s_cselect_b32 s27, s51, s53
	s_add_u32 s6, s6, s85
	s_addc_u32 s7, s7, 0
	s_add_u32 s8, s8, s85
	s_addc_u32 s9, s9, 0
	s_add_u32 s26, s26, s85
	s_addc_u32 s27, s27, 0
	s_mov_b32 m0, s37
	s_nop 0
	global_load_lds_dwordx4 v160, s[6:7]
	s_add_i32 s37, s37, 0x2000
	s_mov_b32 m0, s37
	s_nop 0
	global_load_lds_dwordx4 v160, s[8:9]
	s_add_i32 s37, s37, 0x2000
	s_mov_b32 m0, s37
	s_nop 0
	global_load_lds_dwordx4 v160, s[26:27]
	s_mov_b32 s99, 1
.Lr2_slow_nopf:
	v_lshlrev_b32_e32 v172, 16, v62
	v_and_b32_e32 v173, 0xffff0000, v62
	v_lshlrev_b32_e32 v174, 16, v63
	v_and_b32_e32 v175, 0xffff0000, v63
	v_pk_mul_f32 v[166:167], v[172:173], v[172:173]
	v_pk_mul_f32 v[168:169], v[174:175], v[174:175]
	v_lshlrev_b32_e32 v176, 16, v60
	v_and_b32_e32 v177, 0xffff0000, v60
	v_lshlrev_b32_e32 v178, 16, v61
	v_and_b32_e32 v179, 0xffff0000, v61
	v_pk_fma_f32 v[166:167], v[176:177], v[176:177], v[166:167]
	v_pk_fma_f32 v[168:169], v[178:179], v[178:179], v[168:169]
	v_lshlrev_b32_e32 v180, 16, v58
	v_and_b32_e32 v181, 0xffff0000, v58
	v_lshlrev_b32_e32 v182, 16, v59
	v_and_b32_e32 v183, 0xffff0000, v59
	v_pk_fma_f32 v[166:167], v[180:181], v[180:181], v[166:167]
	v_pk_fma_f32 v[168:169], v[182:183], v[182:183], v[168:169]
	v_lshlrev_b32_e32 v184, 16, v56
	v_and_b32_e32 v185, 0xffff0000, v56
	v_lshlrev_b32_e32 v186, 16, v57
	v_and_b32_e32 v187, 0xffff0000, v57
	v_pk_fma_f32 v[166:167], v[184:185], v[184:185], v[166:167]
	v_pk_fma_f32 v[168:169], v[186:187], v[186:187], v[168:169]
	v_pk_add_f32 v[166:167], v[166:167], v[168:169]
	s_nop 0
	v_add_f32_e32 v164, v166, v167
	v_mov_b32_e32 v165, v164
	s_nop 1
	v_permlane32_swap_b32_e32 v165, v164
	v_add_f32_e32 v164, v164, v165
	v_mov_b32_e32 v165, v164
	s_nop 1
	v_permlane16_swap_b32_e32 v165, v164
	v_add_f32_e32 v164, v164, v165
	s_nop 1
	v_add_f32_dpp v164, v164, v164 row_ror:8 row_mask:0xf bank_mask:0xf
	s_nop 1
	v_add_f32_dpp v164, v164, v164 row_ror:4 row_mask:0xf bank_mask:0xf
	s_nop 1
	v_add_f32_dpp v164, v164, v164 row_ror:2 row_mask:0xf bank_mask:0xf
	s_nop 1
	v_add_f32_dpp v164, v164, v164 row_ror:1 row_mask:0xf bank_mask:0xf
	s_nop 0
	v_fmamk_f32 v164, v164, 0x3a800000, v200
	v_rsq_f32_e32 v164, v164
	s_nop 0
	v_pk_mul_f32 v[172:173], v[172:173], v[164:165] op_sel_hi:[1,0]
	v_pk_mul_f32 v[174:175], v[174:175], v[164:165] op_sel_hi:[1,0]
	v_pk_mul_f32 v[172:173], v[218:219], v[172:173]
	v_pk_mul_f32 v[174:175], v[220:221], v[174:175]
	s_waitcnt lgkmcnt(11)
	v_pk_fma_f32 v[16:17], v[188:189], v[172:173], v[16:17]
	v_pk_fma_f32 v[18:19], v[190:191], v[174:175], v[18:19]
	global_store_dwordx4 v160, v[16:19], s[64:65] nt
	v_pk_mul_f32 v[176:177], v[176:177], v[164:165] op_sel_hi:[1,0]
	v_pk_mul_f32 v[178:179], v[178:179], v[164:165] op_sel_hi:[1,0]
	v_pk_mul_f32 v[176:177], v[222:223], v[176:177]
	v_pk_mul_f32 v[178:179], v[224:225], v[178:179]
	s_waitcnt lgkmcnt(10)
	v_pk_fma_f32 v[20:21], v[192:193], v[176:177], v[20:21]
	v_pk_fma_f32 v[22:23], v[194:195], v[178:179], v[22:23]
	global_store_dwordx4 v160, v[20:23], s[64:65] offset:1024 nt
	v_pk_mul_f32 v[180:181], v[180:181], v[164:165] op_sel_hi:[1,0]
	v_pk_mul_f32 v[182:183], v[182:183], v[164:165] op_sel_hi:[1,0]
	v_pk_mul_f32 v[180:181], v[226:227], v[180:181]
	v_pk_mul_f32 v[182:183], v[228:229], v[182:183]
	s_waitcnt lgkmcnt(9)
	v_pk_fma_f32 v[24:25], v[196:197], v[180:181], v[24:25]
	v_pk_fma_f32 v[26:27], v[198:199], v[182:183], v[26:27]
	global_store_dwordx4 v160, v[24:27], s[64:65] offset:2048 nt
	v_pk_mul_f32 v[184:185], v[184:185], v[164:165] op_sel_hi:[1,0]
	v_pk_mul_f32 v[186:187], v[186:187], v[164:165] op_sel_hi:[1,0]
	v_pk_mul_f32 v[184:185], v[230:231], v[184:185]
	v_pk_mul_f32 v[186:187], v[232:233], v[186:187]
	s_waitcnt lgkmcnt(8)
	v_pk_fma_f32 v[28:29], v[96:97], v[184:185], v[28:29]
	v_pk_fma_f32 v[30:31], v[98:99], v[186:187], v[30:31]
	global_store_dwordx4 v160, v[28:31], s[64:65] offset:3072 nt
	v_pk_mul_f32 v[166:167], v[16:17], v[16:17]
	v_pk_mul_f32 v[168:169], v[18:19], v[18:19]
	v_pk_fma_f32 v[166:167], v[20:21], v[20:21], v[166:167]
	v_pk_fma_f32 v[168:169], v[22:23], v[22:23], v[168:169]
	v_pk_fma_f32 v[166:167], v[24:25], v[24:25], v[166:167]
	v_pk_fma_f32 v[168:169], v[26:27], v[26:27], v[168:169]
	v_pk_fma_f32 v[166:167], v[28:29], v[28:29], v[166:167]
	v_pk_fma_f32 v[168:169], v[30:31], v[30:31], v[168:169]
	v_pk_add_f32 v[166:167], v[166:167], v[168:169]
	s_nop 0
	v_add_f32_e32 v164, v166, v167
	v_mov_b32_e32 v165, v164
	s_nop 1
	v_permlane32_swap_b32_e32 v165, v164
	v_add_f32_e32 v164, v164, v165
	v_mov_b32_e32 v165, v164
	s_nop 1
	v_permlane16_swap_b32_e32 v165, v164
	v_add_f32_e32 v164, v164, v165
	s_nop 1
	v_add_f32_dpp v164, v164, v164 row_ror:8 row_mask:0xf bank_mask:0xf
	s_nop 1
	v_add_f32_dpp v164, v164, v164 row_ror:4 row_mask:0xf bank_mask:0xf
	s_nop 1
	v_add_f32_dpp v164, v164, v164 row_ror:2 row_mask:0xf bank_mask:0xf
	s_nop 1
	v_add_f32_dpp v164, v164, v164 row_ror:1 row_mask:0xf bank_mask:0xf
	s_nop 0
	v_fmamk_f32 v164, v164, 0x3a800000, v200
	v_rsq_f32_e32 v164, v164
	s_nop 0
	v_pk_mul_f32 v[16:17], v[16:17], v[164:165] op_sel_hi:[1,0]
	v_pk_mul_f32 v[18:19], v[18:19], v[164:165] op_sel_hi:[1,0]
	s_waitcnt lgkmcnt(3)
	v_pk_fma_f32 v[80:81], v[234:235], v[80:81], v[234:235]
	v_pk_fma_f32 v[82:83], v[236:237], v[82:83], v[236:237]
	v_pk_fma_f32 v[16:17], v[80:81], v[16:17], v[64:65]
	v_pk_fma_f32 v[18:19], v[82:83], v[18:19], v[66:67]
	v_cvt_pk_bf16_f32 v16, v16, v17
	v_cvt_pk_bf16_f32 v17, v18, v19
	global_store_dwordx2 v[252:253], v[16:17], off
	v_pk_mul_f32 v[20:21], v[20:21], v[164:165] op_sel_hi:[1,0]
	v_pk_mul_f32 v[22:23], v[22:23], v[164:165] op_sel_hi:[1,0]
	s_waitcnt lgkmcnt(2)
	v_pk_fma_f32 v[84:85], v[238:239], v[84:85], v[238:239]
	v_pk_fma_f32 v[86:87], v[240:241], v[86:87], v[240:241]
	v_pk_fma_f32 v[20:21], v[84:85], v[20:21], v[68:69]
	v_pk_fma_f32 v[22:23], v[86:87], v[22:23], v[70:71]
	v_cvt_pk_bf16_f32 v20, v20, v21
	v_cvt_pk_bf16_f32 v21, v22, v23
	global_store_dwordx2 v[252:253], v[20:21], off offset:512
	v_pk_mul_f32 v[24:25], v[24:25], v[164:165] op_sel_hi:[1,0]
	v_pk_mul_f32 v[26:27], v[26:27], v[164:165] op_sel_hi:[1,0]
	s_waitcnt lgkmcnt(1)
	v_pk_fma_f32 v[88:89], v[242:243], v[88:89], v[242:243]
	v_pk_fma_f32 v[90:91], v[244:245], v[90:91], v[244:245]
	v_pk_fma_f32 v[24:25], v[88:89], v[24:25], v[72:73]
	v_pk_fma_f32 v[26:27], v[90:91], v[26:27], v[74:75]
	v_cvt_pk_bf16_f32 v24, v24, v25
	v_cvt_pk_bf16_f32 v25, v26, v27
	global_store_dwordx2 v[252:253], v[24:25], off offset:1024
	v_pk_mul_f32 v[28:29], v[28:29], v[164:165] op_sel_hi:[1,0]
	v_pk_mul_f32 v[30:31], v[30:31], v[164:165] op_sel_hi:[1,0]
	s_waitcnt lgkmcnt(0)
	v_pk_fma_f32 v[92:93], v[246:247], v[92:93], v[246:247]
	v_pk_fma_f32 v[94:95], v[248:249], v[94:95], v[248:249]
	v_pk_fma_f32 v[28:29], v[92:93], v[28:29], v[76:77]
	v_pk_fma_f32 v[30:31], v[94:95], v[30:31], v[78:79]
	v_cvt_pk_bf16_f32 v28, v28, v29
	v_cvt_pk_bf16_f32 v29, v30, v31
	global_store_dwordx2 v[252:253], v[28:29], off offset:1536
	s_xor_b32 s93, s93, 0x6000
	s_branch .LBB0_131

.Lr3_slow_proc:
	s_barrier
	v_add_u32_e32 v37, s93, v160
	ds_read_b128 v[64:67], v37
	ds_read_b128 v[68:71], v37 offset:1024
	ds_read_b128 v[72:75], v37 offset:2048
	ds_read_b128 v[76:79], v37 offset:3072
	ds_read_b128 v[80:83], v37 offset:4096
	ds_read_b128 v[84:87], v37 offset:5120
	ds_read_b128 v[88:91], v37 offset:6144
	ds_read_b128 v[92:95], v37 offset:7168
	v_lshlrev_b32_e32 v172, 16, v54
	v_and_b32_e32 v173, 0xffff0000, v54
	v_lshlrev_b32_e32 v174, 16, v55
	v_and_b32_e32 v175, 0xffff0000, v55
	v_pk_mul_f32 v[166:167], v[172:173], v[172:173]
	v_pk_mul_f32 v[168:169], v[174:175], v[174:175]
	v_lshlrev_b32_e32 v176, 16, v52
	v_and_b32_e32 v177, 0xffff0000, v52
	v_lshlrev_b32_e32 v178, 16, v53
	v_and_b32_e32 v179, 0xffff0000, v53
	v_pk_fma_f32 v[166:167], v[176:177], v[176:177], v[166:167]
	v_pk_fma_f32 v[168:169], v[178:179], v[178:179], v[168:169]
	v_lshlrev_b32_e32 v180, 16, v50
	v_and_b32_e32 v181, 0xffff0000, v50
	v_lshlrev_b32_e32 v182, 16, v51
	v_and_b32_e32 v183, 0xffff0000, v51
	v_pk_fma_f32 v[166:167], v[180:181], v[180:181], v[166:167]
	v_pk_fma_f32 v[168:169], v[182:183], v[182:183], v[168:169]
	v_lshlrev_b32_e32 v184, 16, v48
	v_and_b32_e32 v185, 0xffff0000, v48
	v_lshlrev_b32_e32 v186, 16, v49
	v_and_b32_e32 v187, 0xffff0000, v49
	v_pk_fma_f32 v[166:167], v[184:185], v[184:185], v[166:167]
	v_pk_fma_f32 v[168:169], v[186:187], v[186:187], v[168:169]
	v_pk_add_f32 v[166:167], v[166:167], v[168:169]
	s_nop 0
	v_add_f32_e32 v164, v166, v167
	v_mov_b32_e32 v165, v164
	s_nop 1
	v_permlane32_swap_b32_e32 v165, v164
	v_add_f32_e32 v164, v164, v165
	v_mov_b32_e32 v165, v164
	s_nop 1
	v_permlane16_swap_b32_e32 v165, v164
	v_add_f32_e32 v164, v164, v165
	s_nop 1
	v_add_f32_dpp v164, v164, v164 row_ror:8 row_mask:0xf bank_mask:0xf
	s_nop 1
	v_add_f32_dpp v164, v164, v164 row_ror:4 row_mask:0xf bank_mask:0xf
	s_nop 1
	v_add_f32_dpp v164, v164, v164 row_ror:2 row_mask:0xf bank_mask:0xf
	s_nop 1
	v_add_f32_dpp v164, v164, v164 row_ror:1 row_mask:0xf bank_mask:0xf
	s_nop 0
	v_fmamk_f32 v164, v164, 0x3a800000, v200
	v_rsq_f32_e32 v164, v164
	s_nop 0
	v_pk_mul_f32 v[172:173], v[172:173], v[164:165] op_sel_hi:[1,0]
	v_pk_mul_f32 v[174:175], v[174:175], v[164:165] op_sel_hi:[1,0]
	v_pk_mul_f32 v[172:173], v[218:219], v[172:173]
	v_pk_mul_f32 v[174:175], v[220:221], v[174:175]
	s_waitcnt lgkmcnt(7)
	v_pk_fma_f32 v[12:13], v[64:65], v[172:173], v[12:13]
	v_pk_fma_f32 v[14:15], v[66:67], v[174:175], v[14:15]
	global_store_dwordx4 v160, v[12:15], s[40:41] nt
	v_pk_mul_f32 v[176:177], v[176:177], v[164:165] op_sel_hi:[1,0]
	v_pk_mul_f32 v[178:179], v[178:179], v[164:165] op_sel_hi:[1,0]
	v_pk_mul_f32 v[176:177], v[222:223], v[176:177]
	v_pk_mul_f32 v[178:179], v[224:225], v[178:179]
	s_waitcnt lgkmcnt(6)
	v_pk_fma_f32 v[8:9], v[68:69], v[176:177], v[8:9]
	v_pk_fma_f32 v[10:11], v[70:71], v[178:179], v[10:11]
	global_store_dwordx4 v160, v[8:11], s[40:41] offset:1024 nt
	v_pk_mul_f32 v[180:181], v[180:181], v[164:165] op_sel_hi:[1,0]
	v_pk_mul_f32 v[182:183], v[182:183], v[164:165] op_sel_hi:[1,0]
	v_pk_mul_f32 v[180:181], v[226:227], v[180:181]
	v_pk_mul_f32 v[182:183], v[228:229], v[182:183]
	s_waitcnt lgkmcnt(5)
	v_pk_fma_f32 v[4:5], v[72:73], v[180:181], v[4:5]
	v_pk_fma_f32 v[6:7], v[74:75], v[182:183], v[6:7]
	global_store_dwordx4 v160, v[4:7], s[40:41] offset:2048 nt
	v_pk_mul_f32 v[184:185], v[184:185], v[164:165] op_sel_hi:[1,0]
	v_pk_mul_f32 v[186:187], v[186:187], v[164:165] op_sel_hi:[1,0]
	v_pk_mul_f32 v[184:185], v[230:231], v[184:185]
	v_pk_mul_f32 v[186:187], v[232:233], v[186:187]
	s_waitcnt lgkmcnt(4)
	v_pk_fma_f32 v[0:1], v[76:77], v[184:185], v[0:1]
	v_pk_fma_f32 v[2:3], v[78:79], v[186:187], v[2:3]
	global_store_dwordx4 v160, v[0:3], s[40:41] offset:3072 nt
	s_waitcnt lgkmcnt(0)
	ds_read_b128 v[172:175], v37 offset:8192
	ds_read_b128 v[176:179], v37 offset:9216
	ds_read_b128 v[180:183], v37 offset:10240
	ds_read_b128 v[184:187], v37 offset:11264
	ds_read_b128 v[188:191], v37 offset:12288
	ds_read_b128 v[192:195], v37 offset:13312
	ds_read_b128 v[196:199], v37 offset:14336
	ds_read_b128 v[96:99], v37 offset:15360
	ds_read_b128 v[64:67], v37 offset:16384
	ds_read_b128 v[68:71], v37 offset:17408
	ds_read_b128 v[72:75], v37 offset:18432
	ds_read_b128 v[76:79], v37 offset:19456
	v_add_co_u32_e32 v250, vcc, 0xfbc00000, v46
	v_addc_co_u32_e32 v251, vcc, -1, v47, vcc
	v_pk_mul_f32 v[166:167], v[12:13], v[12:13]
	v_pk_mul_f32 v[168:169], v[14:15], v[14:15]
	v_pk_fma_f32 v[166:167], v[8:9], v[8:9], v[166:167]
	v_pk_fma_f32 v[168:169], v[10:11], v[10:11], v[168:169]
	v_pk_fma_f32 v[166:167], v[4:5], v[4:5], v[166:167]
	v_pk_fma_f32 v[168:169], v[6:7], v[6:7], v[168:169]
	v_pk_fma_f32 v[166:167], v[0:1], v[0:1], v[166:167]
	v_pk_fma_f32 v[168:169], v[2:3], v[2:3], v[168:169]
	v_pk_add_f32 v[166:167], v[166:167], v[168:169]
	s_nop 0
	v_add_f32_e32 v164, v166, v167
	v_mov_b32_e32 v165, v164
	s_nop 1
	v_permlane32_swap_b32_e32 v165, v164
	v_add_f32_e32 v164, v164, v165
	v_mov_b32_e32 v165, v164
	s_nop 1
	v_permlane16_swap_b32_e32 v165, v164
	v_add_f32_e32 v164, v164, v165
	s_nop 1
	v_add_f32_dpp v164, v164, v164 row_ror:8 row_mask:0xf bank_mask:0xf
	s_nop 1
	v_add_f32_dpp v164, v164, v164 row_ror:4 row_mask:0xf bank_mask:0xf
	s_nop 1
	v_add_f32_dpp v164, v164, v164 row_ror:2 row_mask:0xf bank_mask:0xf
	s_nop 1
	v_add_f32_dpp v164, v164, v164 row_ror:1 row_mask:0xf bank_mask:0xf
	s_nop 0
	v_fmamk_f32 v164, v164, 0x3a800000, v200
	v_rsq_f32_e32 v164, v164
	s_nop 0
	v_pk_mul_f32 v[12:13], v[12:13], v[164:165] op_sel_hi:[1,0]
	v_pk_mul_f32 v[14:15], v[14:15], v[164:165] op_sel_hi:[1,0]
	s_waitcnt lgkmcnt(11)
	v_pk_fma_f32 v[172:173], v[234:235], v[172:173], v[234:235]
	v_pk_fma_f32 v[174:175], v[236:237], v[174:175], v[236:237]
	v_pk_fma_f32 v[12:13], v[172:173], v[12:13], v[80:81]
	v_pk_fma_f32 v[14:15], v[174:175], v[14:15], v[82:83]
	v_cvt_pk_bf16_f32 v12, v12, v13
	v_cvt_pk_bf16_f32 v13, v14, v15
	global_store_dwordx2 v[250:251], v[12:13], off offset:-1536
	ds_read_b128 v[80:83], v37 offset:20480
	v_pk_mul_f32 v[8:9], v[8:9], v[164:165] op_sel_hi:[1,0]
	v_pk_mul_f32 v[10:11], v[10:11], v[164:165] op_sel_hi:[1,0]
	s_waitcnt lgkmcnt(11)
	v_pk_fma_f32 v[176:177], v[238:239], v[176:177], v[238:239]
	v_pk_fma_f32 v[178:179], v[240:241], v[178:179], v[240:241]
	v_pk_fma_f32 v[8:9], v[176:177], v[8:9], v[84:85]
	v_pk_fma_f32 v[10:11], v[178:179], v[10:11], v[86:87]
	v_cvt_pk_bf16_f32 v8, v8, v9
	v_cvt_pk_bf16_f32 v9, v10, v11
	global_store_dwordx2 v[250:251], v[8:9], off offset:-1024
	ds_read_b128 v[84:87], v37 offset:21504
	v_pk_mul_f32 v[4:5], v[4:5], v[164:165] op_sel_hi:[1,0]
	v_pk_mul_f32 v[6:7], v[6:7], v[164:165] op_sel_hi:[1,0]
	s_waitcnt lgkmcnt(11)
	v_pk_fma_f32 v[180:181], v[242:243], v[180:181], v[242:243]
	v_pk_fma_f32 v[182:183], v[244:245], v[182:183], v[244:245]
	v_pk_fma_f32 v[4:5], v[180:181], v[4:5], v[88:89]
	v_pk_fma_f32 v[6:7], v[182:183], v[6:7], v[90:91]
	v_cvt_pk_bf16_f32 v4, v4, v5
	v_cvt_pk_bf16_f32 v5, v6, v7
	global_store_dwordx2 v[250:251], v[4:5], off offset:-512
	ds_read_b128 v[88:91], v37 offset:22528
	v_pk_mul_f32 v[0:1], v[0:1], v[164:165] op_sel_hi:[1,0]
	v_pk_mul_f32 v[2:3], v[2:3], v[164:165] op_sel_hi:[1,0]
	s_waitcnt lgkmcnt(11)
	v_pk_fma_f32 v[184:185], v[246:247], v[184:185], v[246:247]
	v_pk_fma_f32 v[186:187], v[248:249], v[186:187], v[248:249]
	v_pk_fma_f32 v[0:1], v[184:185], v[0:1], v[92:93]
	v_pk_fma_f32 v[2:3], v[186:187], v[2:3], v[94:95]
	v_cvt_pk_bf16_f32 v0, v0, v1
	v_cvt_pk_bf16_f32 v1, v2, v3
	global_store_dwordx2 v[250:251], v[0:1], off
	ds_read_b128 v[92:95], v37 offset:23552
	s_waitcnt vmcnt(8)
	s_mov_b32 s99, 0
	s_add_i32 s72, s19, s48
	s_cmp_gt_i32 s72, 0x87ff
	s_cbranch_scc1 .Lr3_slow_nopf
	s_add_i32 s8, s44, s72
	s_cmp_lt_i32 s8, 0x8800
	s_cbranch_scc0 .Lr3_slow_nopf
	s_mov_b32 s41, s72
	s_mul_hi_i32 s6, s41, 0x78787879
	s_lshr_b32 s7, s6, 31
	s_ashr_i32 s6, s6, 11
	s_add_i32 s6, s6, s7
	s_mul_i32 s7, s6, 0xffffef00
	s_add_i32 s7, s41, s7
	s_cmpk_gt_i32 s7, 0xff
	s_cselect_b64 s[50:51], -1, 0
	s_mul_hi_i32 s9, s8, 0x78787879
	s_lshr_b32 s25, s9, 31
	s_ashr_i32 s9, s9, 11
	s_add_i32 s9, s9, s25
	s_mul_i32 s25, s9, 0xffffef00
	s_add_i32 s25, s8, s25
	s_cmpk_gt_i32 s25, 0xff
	s_cselect_b64 s[52:53], -1, 0
	s_cmp_lg_u64 s[4:5], 0
	s_cbranch_scc0 .Lr3_slow_nopf
	s_add_i32 s72, s7, 0xffffff00
	s_cmp_lg_u64 s[50:51], 0
	s_cselect_b32 s27, s22, s49
	s_cselect_b32 s32, s23, s55
	s_cselect_b32 s37, 24, 20
	s_cselect_b32 s72, s72, s7
	s_cselect_b32 s85, s6, 8
	s_mov_b32 s40, s6
	s_mov_b32 s41, 0
	s_lshl_b64 s[40:41], s[40:41], s37
	s_add_u32 s40, s27, s40
	s_addc_u32 s41, s32, s41
	s_lshl_b32 s72, s72, 12
	s_add_u32 s40, s40, s72
	s_addc_u32 s41, s41, 0
	s_add_i32 s27, s85, s3
	s_mul_hi_i32 s32, s27, 0x6000
	s_mulk_i32 s27, 0x6000
	s_add_u32 s66, s34, s27
	s_addc_u32 s67, s35, s32
	s_add_u32 s66, s66, 0x5000
	s_addc_u32 s67, s67, 0
	s_add_i32 s27, s85, s13
	s_mul_hi_i32 s32, s27, 0x6000
	s_mulk_i32 s27, 0x6000
	s_add_u32 s38, s34, s27
	s_addc_u32 s39, s35, s32
	s_add_u32 s46, s38, 0x1000
	s_addc_u32 s47, s39, 0
	s_mov_b64 s[6:7], s[52:53]
	s_cmp_lg_u64 s[6:7], 0
	s_cselect_b32 s85, s9, 8
	s_add_i32 s27, s85, s3
	s_mul_hi_i32 s32, s27, 0x6000
	s_mulk_i32 s27, 0x6000
	s_add_u32 s10, s34, s27
	s_addc_u32 s11, s35, s32
	s_add_u32 s10, s10, 0x5000
	s_addc_u32 s11, s11, 0
	s_add_i32 s27, s85, s13
	s_mul_hi_i32 s32, s27, 0x6000
	s_mulk_i32 s27, 0x6000
	s_add_u32 s50, s34, s27
	s_addc_u32 s51, s35, s32
	s_add_u32 s52, s50, 0x1000
	s_addc_u32 s53, s51, 0
	s_xor_b32 s25, s93, 0x6000
	v_lshl_add_u64 v[250:251], v[46:47], 0, s[74:75]
	global_load_dwordx4 v[12:15], v160, s[40:41] nt
	global_load_dwordx4 v[8:11], v160, s[40:41] offset:1024 nt
	global_load_dwordx4 v[4:7], v160, s[40:41] offset:2048 nt
	global_load_dwordx4 v[0:3], v160, s[40:41] offset:3072 nt
	global_load_dwordx2 v[54:55], v[250:251], off offset:-1536 nt
	global_load_dwordx2 v[52:53], v[250:251], off offset:-1024 nt
	global_load_dwordx2 v[50:51], v[250:251], off offset:-512 nt
	global_load_dwordx2 v[48:49], v[250:251], off nt
	s_and_b32 s72, s19, 7
	s_and_b32 s85, s72, 3
	s_lshl_b32 s85, s85, 10
	s_lshl_b32 s37, s72, 10
	s_add_i32 s37, s37, s25
	s_cmp_lt_u32 s72, 4
	s_cselect_b32 s6, s66, s38
	s_cselect_b32 s7, s67, s39
	s_cselect_b32 s8, s46, s10
	s_cselect_b32 s9, s47, s11
	s_cselect_b32 s26, s50, s52
	s_cselect_b32 s27, s51, s53
	s_add_u32 s6, s6, s85
	s_addc_u32 s7, s7, 0
	s_add_u32 s8, s8, s85
	s_addc_u32 s9, s9, 0
	s_add_u32 s26, s26, s85
	s_addc_u32 s27, s27, 0
	s_mov_b32 m0, s37
	s_nop 0
	global_load_lds_dwordx4 v160, s[6:7]
	s_add_i32 s37, s37, 0x2000
	s_mov_b32 m0, s37
	s_nop 0
	global_load_lds_dwordx4 v160, s[8:9]
	s_add_i32 s37, s37, 0x2000
	s_mov_b32 m0, s37
	s_nop 0
	global_load_lds_dwordx4 v160, s[26:27]
	s_mov_b32 s99, 1
